# P0 sampled-absmax items: software-pipelined the four 8-load rounds (next round's loads issued before the previous round is consumed, counted vmcnt)
# speedup vs baseline: 1.0016x; 1.0016x over previous
; __device__ __forceinline__ float p0_absmax_item(const float* W, int K, int N, int item, int lane, int nmin) {
;     (void)K; const int nblk = (N + 31) / 32, kb = item / nblk, nb = item % nblk, k0 = 64 * kb, n0 = 32 * nb;
;     const int nn = n0 + (lane & 31); const bool okr = nn < N && nn >= nmin;
;     float m = 0.f;
; #pragma unroll
;     for (int i = 0; i < 32; ++i) { const int kk = 2 * i + (lane >> 5); m = fmaxf(m, fabsf(okr ? W[(size_t)(k0 + kk) * N + nn] : 0.f)); }
;     return m;
.LBB0_57:
	v_lshlrev_b32_e32 v6, 2, v2
	v_lshl_add_u64 v[22:23], s[34:35], 0, v[6:7]
	s_waitcnt lgkmcnt(0)
	v_mov_b32_e32 v11, v7
	v_lshl_add_u64 v[22:23], v[22:23], 0, v[10:11]
	v_add_co_u32_e32 v24, vcc, 0x9000, v22
	s_nop 1
	v_addc_co_u32_e32 v25, vcc, 0, v23, vcc
	v_add_co_u32_e32 v26, vcc, 0x27000, v22
	s_nop 1
	v_addc_co_u32_e32 v27, vcc, 0, v23, vcc
	v_add_co_u32_e32 v28, vcc, 0x45000, v22
	s_nop 1
	v_addc_co_u32_e32 v29, vcc, 0, v23, vcc
	v_add_co_u32_e32 v98, vcc, 0x63000, v22
	s_nop 1
	v_addc_co_u32_e32 v99, vcc, 0, v23, vcc
	v_add_co_u32_e32 v100, vcc, 0x81000, v22
	s_nop 1
	v_addc_co_u32_e32 v101, vcc, 0, v23, vcc
	v_add_co_u32_e32 v102, vcc, 0x9f000, v22
	s_nop 1
	v_addc_co_u32_e32 v103, vcc, 0, v23, vcc
	v_add_co_u32_e32 v104, vcc, 0xbd000, v22
	s_nop 1
	v_addc_co_u32_e32 v105, vcc, 0, v23, vcc
	v_add_co_u32_e32 v106, vcc, 0xdb000, v22
	s_nop 1
	v_addc_co_u32_e32 v107, vcc, 0, v23, vcc
	global_load_dword v6, v[24:25], off offset:128
	global_load_dword v11, v[26:27], off offset:256
	global_load_dword v21, v[28:29], off offset:384
	global_load_dword v97, v[98:99], off offset:512
	global_load_dword v108, v[100:101], off offset:640
	global_load_dword v109, v[102:103], off offset:768
	global_load_dword v110, v[104:105], off offset:896
	global_load_dword v111, v[106:107], off offset:1024
	v_add_co_u32_e32 v24, vcc, 0xf9000, v22
	s_nop 1
	v_addc_co_u32_e32 v25, vcc, 0, v23, vcc
	v_add_co_u32_e32 v26, vcc, 0x117000, v22
	s_nop 1
	v_addc_co_u32_e32 v27, vcc, 0, v23, vcc
	v_add_co_u32_e32 v28, vcc, 0x135000, v22
	s_nop 1
	v_addc_co_u32_e32 v29, vcc, 0, v23, vcc
	v_add_co_u32_e32 v98, vcc, 0x153000, v22
	s_nop 1
	v_addc_co_u32_e32 v99, vcc, 0, v23, vcc
	v_add_co_u32_e32 v100, vcc, 0x171000, v22
	s_nop 1
	v_addc_co_u32_e32 v101, vcc, 0, v23, vcc
	v_add_co_u32_e32 v102, vcc, 0x18f000, v22
	s_nop 1
	v_addc_co_u32_e32 v103, vcc, 0, v23, vcc
	v_add_co_u32_e32 v104, vcc, 0x1ad000, v22
	s_nop 1
	v_addc_co_u32_e32 v105, vcc, 0, v23, vcc
	v_add_co_u32_e32 v106, vcc, 0x1cb000, v22
	s_nop 1
	v_addc_co_u32_e32 v107, vcc, 0, v23, vcc
	global_load_dword v112, v[24:25], off offset:1152
	global_load_dword v113, v[26:27], off offset:1280
	global_load_dword v114, v[28:29], off offset:1408
	global_load_dword v115, v[98:99], off offset:1536
	global_load_dword v116, v[100:101], off offset:1664
	global_load_dword v117, v[102:103], off offset:1792
	global_load_dword v118, v[104:105], off offset:1920
	global_load_dword v119, v[106:107], off offset:2048
	s_waitcnt vmcnt(14)
	v_max3_f32 v6, |v6|, 0, |v11|
	s_waitcnt vmcnt(12)
	v_max3_f32 v6, v6, |v21|, |v97|
	s_waitcnt vmcnt(10)
	v_max3_f32 v6, v6, |v108|, |v109|
	s_waitcnt vmcnt(8)
	v_max3_f32 v6, v6, |v110|, |v111|
	v_add_co_u32_e32 v24, vcc, 0x1e9000, v22
	s_nop 1
	v_addc_co_u32_e32 v25, vcc, 0, v23, vcc
	v_add_co_u32_e32 v26, vcc, 0x207000, v22
	s_nop 1
	v_addc_co_u32_e32 v27, vcc, 0, v23, vcc
	v_add_co_u32_e32 v28, vcc, 0x225000, v22
	s_nop 1
	v_addc_co_u32_e32 v29, vcc, 0, v23, vcc
	v_add_co_u32_e32 v98, vcc, 0x243000, v22
	s_nop 1
	v_addc_co_u32_e32 v99, vcc, 0, v23, vcc
	v_add_co_u32_e32 v100, vcc, 0x261000, v22
	s_nop 1
	v_addc_co_u32_e32 v101, vcc, 0, v23, vcc
	v_add_co_u32_e32 v102, vcc, 0x27f000, v22
	s_nop 1
	v_addc_co_u32_e32 v103, vcc, 0, v23, vcc
	v_add_co_u32_e32 v104, vcc, 0x29d000, v22
	s_nop 1
	v_addc_co_u32_e32 v105, vcc, 0, v23, vcc
	v_add_co_u32_e32 v106, vcc, 0x2bb000, v22
	s_nop 1
	v_addc_co_u32_e32 v107, vcc, 0, v23, vcc
	global_load_dword v120, v[24:25], off offset:2176
	global_load_dword v121, v[26:27], off offset:2304
	global_load_dword v122, v[28:29], off offset:2432
	global_load_dword v123, v[98:99], off offset:2560
	global_load_dword v124, v[100:101], off offset:2688
	global_load_dword v125, v[102:103], off offset:2816
	global_load_dword v126, v[104:105], off offset:2944
	s_nop 0
	global_load_dword v106, v[106:107], off offset:3072
	s_waitcnt vmcnt(14)
; __device__ __forceinline__ float p0_absmax_item(const float* W, int K, int N, int item, int lane, int nmin) {
;     ...
; #pragma unroll
;     for (int i = 0; i < 32; ++i) { const int kk = 2 * i + (lane >> 5); m = fmaxf(m, fabsf(okr ? W[(size_t)(k0 + kk) * N + nn] : 0.f)); }
;     return m;
	v_max3_f32 v6, v6, |v112|, |v113|
	s_waitcnt vmcnt(12)
	v_max3_f32 v6, v6, |v114|, |v115|
	s_waitcnt vmcnt(10)
	v_max3_f32 v6, v6, |v116|, |v117|
	s_waitcnt vmcnt(8)
	v_max3_f32 v6, v6, |v118|, |v119|
	v_add_co_u32_e32 v24, vcc, 0x2d9000, v22
	s_nop 1
	v_addc_co_u32_e32 v25, vcc, 0, v23, vcc
	v_add_co_u32_e32 v26, vcc, 0x2f7000, v22
	s_nop 1
	v_addc_co_u32_e32 v27, vcc, 0, v23, vcc
	v_add_co_u32_e32 v28, vcc, 0x315000, v22
	s_nop 1
	v_addc_co_u32_e32 v29, vcc, 0, v23, vcc
	v_add_co_u32_e32 v98, vcc, 0x333000, v22
	s_nop 1
	v_addc_co_u32_e32 v99, vcc, 0, v23, vcc
	v_add_co_u32_e32 v100, vcc, 0x351000, v22
	s_nop 1
	v_addc_co_u32_e32 v101, vcc, 0, v23, vcc
	v_add_co_u32_e32 v102, vcc, 0x36f000, v22
	s_nop 1
	v_addc_co_u32_e32 v103, vcc, 0, v23, vcc
	v_add_co_u32_e32 v104, vcc, 0x38d000, v22
	s_nop 1
	v_addc_co_u32_e32 v105, vcc, 0, v23, vcc
	v_add_co_u32_e32 v22, vcc, 0x3ac000, v22
	s_nop 1
	v_addc_co_u32_e32 v23, vcc, 0, v23, vcc
	global_load_dword v24, v[24:25], off offset:3200
	s_nop 0
	global_load_dword v25, v[26:27], off offset:3328
	s_nop 0
	global_load_dword v26, v[28:29], off offset:3456
	global_load_dword v27, v[98:99], off offset:3584
	s_nop 0
	global_load_dword v28, v[100:101], off offset:3712
	global_load_dword v29, v[102:103], off offset:3840
	global_load_dword v98, v[104:105], off offset:3968
	s_nop 0
	global_load_dword v22, v[22:23], off
	s_waitcnt vmcnt(14)
	v_max3_f32 v6, v6, |v120|, |v121|
	s_waitcnt vmcnt(12)
	v_max3_f32 v6, v6, |v122|, |v123|
	s_waitcnt vmcnt(10)
	v_max3_f32 v6, v6, |v124|, |v125|
	s_waitcnt vmcnt(8)
	v_max3_f32 v6, v6, |v126|, |v106|
	v_cmp_lt_i32_e32 vcc, v14, v16
	s_waitcnt vmcnt(6)
	v_max3_f32 v6, v6, |v24|, |v25|
	v_cndmask_b32_e32 v11, v93, v14, vcc
	s_waitcnt vmcnt(4)
	v_max3_f32 v6, v6, |v26|, |v27|
	v_lshlrev_b32_e32 v11, 2, v11
	s_waitcnt vmcnt(2)
	v_max3_f32 v6, v6, |v28|, |v29|
	v_cmp_lt_i32_e32 vcc, v15, v16
	s_waitcnt vmcnt(0)
	v_max3_f32 v6, v6, |v98|, |v22|
	ds_bpermute_b32 v11, v11, v6
	s_waitcnt lgkmcnt(0)
	v_max_f32_e32 v11, v11, v11
	v_max_f32_e32 v6, v6, v11
	v_cndmask_b32_e32 v11, v93, v15, vcc
	v_lshlrev_b32_e32 v11, 2, v11
	ds_bpermute_b32 v11, v11, v6
	v_cmp_lt_i32_e32 vcc, v17, v16
	s_waitcnt lgkmcnt(0)
	v_max_f32_e32 v11, v11, v11
	v_max_f32_e32 v6, v6, v11
	v_cndmask_b32_e32 v11, v93, v17, vcc
	v_lshlrev_b32_e32 v11, 2, v11
	ds_bpermute_b32 v11, v11, v6
	v_cmp_lt_i32_e32 vcc, v18, v16
	s_waitcnt lgkmcnt(0)
	v_max_f32_e32 v11, v11, v11
	v_max_f32_e32 v6, v6, v11
	v_cndmask_b32_e32 v11, v93, v18, vcc
	v_lshlrev_b32_e32 v11, 2, v11
	ds_bpermute_b32 v11, v11, v6
	v_cmp_lt_i32_e32 vcc, v19, v16
	s_waitcnt lgkmcnt(0)
	v_max_f32_e32 v11, v11, v11
	v_max_f32_e32 v6, v6, v11
	v_cndmask_b32_e32 v11, v93, v19, vcc
	v_lshlrev_b32_e32 v11, 2, v11
	ds_bpermute_b32 v11, v11, v6
	v_cmp_lt_i32_e32 vcc, v20, v16
	s_waitcnt lgkmcnt(0)
	v_max_f32_e32 v11, v11, v11
	v_max_f32_e32 v6, v6, v11
	v_cndmask_b32_e32 v11, v93, v20, vcc
	v_lshlrev_b32_e32 v11, 2, v11
	ds_bpermute_b32 v11, v11, v6
	s_waitcnt lgkmcnt(0)
	v_max_f32_e32 v11, v11, v11
	v_max_f32_e32 v14, v6, v11
	v_mul_f32_e32 v6, 0x41000000, v14
	v_max_f32_e32 v6, 0xda24260, v6
	v_div_scale_f32 v11, s[30:31], v6, v6, s47
	v_rcp_f32_e32 v15, v11
	s_nop 0
	v_fma_f32 v16, -v11, v15, 1.0
	v_fmac_f32_e32 v15, v16, v15
	v_div_scale_f32 v16, vcc, s47, v6, s47
	v_mul_f32_e32 v17, v16, v15
	v_fma_f32 v18, -v11, v17, v16
	v_fmac_f32_e32 v17, v18, v15
	v_fma_f32 v11, -v11, v17, v16
	v_div_fmas_f32 v11, v11, v15, v17
	s_and_saveexec_b64 s[30:31], s[38:39]
	s_cbranch_execz .LBB0_62
	s_mov_b64 s[36:37], exec
	s_mov_b32 s40, 0

; __device__ __forceinline__ float p0_absmax_item(const float* W, int K, int N, int item, int lane, int nmin) {
;     (void)K; const int nblk = (N + 31) / 32, kb = item / nblk, nb = item % nblk, k0 = 64 * kb, n0 = 32 * nb;
;     const int nn = n0 + (lane & 31); const bool okr = nn < N && nn >= nmin;
;     float m = 0.f;
; #pragma unroll
;     for (int i = 0; i < 32; ++i) { const int kk = 2 * i + (lane >> 5); m = fmaxf(m, fabsf(okr ? W[(size_t)(k0 + kk) * N + nn] : 0.f)); }
;     return m;
.LBB0_202:
	s_load_dwordx2 s[12:13], s[14:15], 0xe0
	s_lshl_b64 s[30:31], s[26:27], 2
	v_lshlrev_b32_e32 v6, 2, v2
	s_waitcnt lgkmcnt(0)
	s_add_u32 s12, s12, s30
	s_addc_u32 s13, s13, s31
	v_lshl_add_u64 v[20:21], s[12:13], 0, v[6:7]
	v_lshlrev_b32_e32 v6, 2, v12
	v_lshl_add_u64 v[20:21], v[20:21], 0, v[6:7]
	s_movk_i32 s12, 0x4000
	v_add_co_u32_e32 v22, vcc, 0x4000, v20
	s_nop 1
	v_addc_co_u32_e32 v23, vcc, 0, v21, vcc
	v_add_co_u32_e32 v24, vcc, 0x8000, v20
	s_nop 1
	v_addc_co_u32_e32 v25, vcc, 0, v21, vcc
	v_add_co_u32_e32 v26, vcc, 0xc000, v20
	s_nop 1
	v_addc_co_u32_e32 v27, vcc, 0, v21, vcc
	v_add_co_u32_e32 v28, vcc, 0x10000, v20
	s_nop 1
	v_addc_co_u32_e32 v29, vcc, 0, v21, vcc
	v_add_co_u32_e32 v98, vcc, 0x14000, v20
	s_nop 1
	v_addc_co_u32_e32 v99, vcc, 0, v21, vcc
	v_add_co_u32_e32 v100, vcc, 0x18000, v20
	s_nop 1
	v_addc_co_u32_e32 v101, vcc, 0, v21, vcc
	v_add_co_u32_e32 v102, vcc, 0x1c000, v20
	s_nop 1
	v_addc_co_u32_e32 v103, vcc, 0, v21, vcc
	global_load_dword v6, v[20:21], off
	global_load_dword v97, v[22:23], off
	global_load_dword v106, v[24:25], off
	global_load_dword v107, v[26:27], off
	global_load_dword v108, v[28:29], off
	global_load_dword v109, v[98:99], off
	global_load_dword v110, v[100:101], off
	global_load_dword v111, v[102:103], off
	v_add_co_u32_e32 v22, vcc, 0x20000, v20
	s_nop 1
	v_addc_co_u32_e32 v23, vcc, 0, v21, vcc
	v_add_co_u32_e32 v24, vcc, 0x24000, v20
	s_nop 1
	v_addc_co_u32_e32 v25, vcc, 0, v21, vcc
	v_add_co_u32_e32 v26, vcc, 0x28000, v20
	s_nop 1
	v_addc_co_u32_e32 v27, vcc, 0, v21, vcc
	v_add_co_u32_e32 v28, vcc, s60, v20
	s_nop 1
	v_addc_co_u32_e32 v29, vcc, 0, v21, vcc
	v_add_co_u32_e32 v98, vcc, 0x30000, v20
	s_nop 1
	v_addc_co_u32_e32 v99, vcc, 0, v21, vcc
	v_add_co_u32_e32 v100, vcc, 0x34000, v20
	s_nop 1
	v_addc_co_u32_e32 v101, vcc, 0, v21, vcc
	v_add_co_u32_e32 v102, vcc, s63, v20
	s_nop 1
	v_addc_co_u32_e32 v103, vcc, 0, v21, vcc
	v_add_co_u32_e32 v104, vcc, s64, v20
	s_nop 1
	v_addc_co_u32_e32 v105, vcc, 0, v21, vcc
	global_load_dword v112, v[22:23], off
	global_load_dword v113, v[24:25], off
	global_load_dword v114, v[26:27], off
	global_load_dword v115, v[28:29], off
	global_load_dword v116, v[98:99], off
	global_load_dword v117, v[100:101], off
	global_load_dword v118, v[102:103], off
	global_load_dword v119, v[104:105], off
	s_waitcnt vmcnt(14)
	v_max3_f32 v6, |v6|, 0, |v97|
	s_waitcnt vmcnt(12)
	v_max3_f32 v6, v6, |v106|, |v107|
	s_waitcnt vmcnt(10)
	v_max3_f32 v6, v6, |v108|, |v109|
	s_waitcnt vmcnt(8)
	v_max3_f32 v6, v6, |v110|, |v111|
	v_add_co_u32_e32 v22, vcc, s65, v20
	s_nop 1
	v_addc_co_u32_e32 v23, vcc, 0, v21, vcc
	v_add_co_u32_e32 v24, vcc, s66, v20
	s_nop 1
	v_addc_co_u32_e32 v25, vcc, 0, v21, vcc
	v_add_co_u32_e32 v26, vcc, s67, v20
	s_nop 1
	v_addc_co_u32_e32 v27, vcc, 0, v21, vcc
	v_add_co_u32_e32 v28, vcc, s68, v20
	s_nop 1
	v_addc_co_u32_e32 v29, vcc, 0, v21, vcc
	v_add_co_u32_e32 v98, vcc, s69, v20
	s_nop 1
	v_addc_co_u32_e32 v99, vcc, 0, v21, vcc
	v_add_co_u32_e32 v100, vcc, s72, v20
	s_nop 1
	v_addc_co_u32_e32 v101, vcc, 0, v21, vcc
	v_add_co_u32_e32 v102, vcc, s73, v20
	s_nop 1
	v_addc_co_u32_e32 v103, vcc, 0, v21, vcc
	v_add_co_u32_e32 v104, vcc, s74, v20
	s_nop 1
	v_addc_co_u32_e32 v105, vcc, 0, v21, vcc
	global_load_dword v120, v[22:23], off
	global_load_dword v121, v[24:25], off
	global_load_dword v122, v[26:27], off
	global_load_dword v123, v[28:29], off
	global_load_dword v124, v[98:99], off
	global_load_dword v125, v[100:101], off
	global_load_dword v126, v[102:103], off
	s_nop 0
	global_load_dword v104, v[104:105], off
	s_waitcnt vmcnt(14)
	v_max3_f32 v6, v6, |v112|, |v113|
	s_waitcnt vmcnt(12)
	v_max3_f32 v6, v6, |v114|, |v115|
	s_waitcnt vmcnt(10)
	v_max3_f32 v6, v6, |v116|, |v117|
	s_waitcnt vmcnt(8)
	v_max3_f32 v6, v6, |v118|, |v119|
	v_add_co_u32_e32 v22, vcc, s75, v20
	s_nop 1
	v_addc_co_u32_e32 v23, vcc, 0, v21, vcc
	v_add_co_u32_e32 v24, vcc, s76, v20
	s_nop 1
	v_addc_co_u32_e32 v25, vcc, 0, v21, vcc
	v_add_co_u32_e32 v26, vcc, s77, v20
	s_nop 1
	v_addc_co_u32_e32 v27, vcc, 0, v21, vcc
	v_add_co_u32_e32 v28, vcc, s78, v20
	s_nop 1
	v_addc_co_u32_e32 v29, vcc, 0, v21, vcc
	v_add_co_u32_e32 v98, vcc, s79, v20
	s_nop 1
	v_addc_co_u32_e32 v99, vcc, 0, v21, vcc
	v_add_co_u32_e32 v100, vcc, s80, v20
	s_nop 1
	v_addc_co_u32_e32 v101, vcc, 0, v21, vcc
	v_add_co_u32_e32 v102, vcc, s81, v20
	s_nop 1
	v_addc_co_u32_e32 v103, vcc, 0, v21, vcc
	v_add_co_u32_e32 v20, vcc, s82, v20
	s_nop 1
	v_addc_co_u32_e32 v21, vcc, 0, v21, vcc
	global_load_dword v22, v[22:23], off
	s_nop 0
	global_load_dword v23, v[24:25], off
	s_nop 0
	global_load_dword v24, v[26:27], off
	global_load_dword v25, v[28:29], off
	s_nop 0
	global_load_dword v26, v[98:99], off
	global_load_dword v27, v[100:101], off
	global_load_dword v28, v[102:103], off
	s_nop 0
	global_load_dword v20, v[20:21], off
	s_waitcnt vmcnt(14)
	v_max3_f32 v6, v6, |v120|, |v121|
	s_waitcnt vmcnt(12)
	v_max3_f32 v6, v6, |v122|, |v123|
	s_waitcnt vmcnt(10)
	v_max3_f32 v6, v6, |v124|, |v125|
	s_waitcnt vmcnt(8)
	v_max3_f32 v6, v6, |v126|, |v104|
	s_mov_b32 s12, 0x34000
	v_cmp_lt_i32_e32 vcc, v19, v11
	s_waitcnt vmcnt(6)
	v_max3_f32 v6, v6, |v22|, |v23|
	v_cndmask_b32_e32 v19, v93, v19, vcc
	s_waitcnt vmcnt(4)
	v_max3_f32 v6, v6, |v24|, |v25|
	v_lshlrev_b32_e32 v19, 2, v19
	s_waitcnt vmcnt(2)
	v_max3_f32 v6, v6, |v26|, |v27|
	v_cmp_lt_i32_e32 vcc, v18, v11
	s_waitcnt vmcnt(0)
	v_max3_f32 v6, v6, |v28|, |v20|
	ds_bpermute_b32 v19, v19, v6
	v_cndmask_b32_e32 v18, v93, v18, vcc
	v_lshlrev_b32_e32 v18, 2, v18
	v_cmp_lt_i32_e32 vcc, v17, v11
	s_waitcnt lgkmcnt(0)
	v_max_f32_e32 v19, v19, v19
	v_max_f32_e32 v6, v6, v19
	ds_bpermute_b32 v18, v18, v6
	v_cndmask_b32_e32 v17, v93, v17, vcc
	v_lshlrev_b32_e32 v17, 2, v17
	v_cmp_lt_i32_e32 vcc, v16, v11
	s_waitcnt lgkmcnt(0)
	v_max_f32_e32 v18, v18, v18
	v_max_f32_e32 v6, v6, v18
	ds_bpermute_b32 v17, v17, v6
	v_cndmask_b32_e32 v16, v93, v16, vcc
	v_lshlrev_b32_e32 v16, 2, v16
	v_cmp_lt_i32_e32 vcc, v15, v11
	s_waitcnt lgkmcnt(0)
	v_max_f32_e32 v17, v17, v17
	v_max_f32_e32 v6, v6, v17
	ds_bpermute_b32 v16, v16, v6
	v_cndmask_b32_e32 v15, v93, v15, vcc
	v_lshlrev_b32_e32 v15, 2, v15
	v_cmp_lt_i32_e32 vcc, v14, v11
	s_waitcnt lgkmcnt(0)
	v_max_f32_e32 v16, v16, v16
	v_max_f32_e32 v6, v6, v16
	ds_bpermute_b32 v15, v15, v6
	v_cndmask_b32_e32 v11, v93, v14, vcc
	v_lshlrev_b32_e32 v11, 2, v11
	s_waitcnt lgkmcnt(0)
	v_max_f32_e32 v15, v15, v15
	v_max_f32_e32 v6, v6, v15
	ds_bpermute_b32 v11, v11, v6
	s_waitcnt lgkmcnt(0)
	v_max_f32_e32 v11, v11, v11
	v_max_f32_e32 v14, v6, v11
	v_mul_f32_e32 v6, 0x41000000, v14
	v_max_f32_e32 v6, 0xda24260, v6
	v_div_scale_f32 v11, s[12:13], v6, v6, s47
	v_rcp_f32_e32 v15, v11
	s_nop 0
	v_fma_f32 v16, -v11, v15, 1.0
	v_fmac_f32_e32 v15, v16, v15
	v_div_scale_f32 v16, vcc, s47, v6, s47
	v_mul_f32_e32 v17, v16, v15
	v_fma_f32 v18, -v11, v17, v16
	v_fmac_f32_e32 v17, v18, v15
	v_fma_f32 v11, -v11, v17, v16
	v_div_fmas_f32 v11, v11, v15, v17
	s_and_saveexec_b64 s[30:31], s[38:39]
	s_cbranch_execz .LBB0_207
	s_mov_b64 s[36:37], exec
	s_mov_b32 s12, 0

; __device__ __forceinline__ float p0_absmax_item(const float* W, int K, int N, int item, int lane, int nmin) {
;     (void)K; const int nblk = (N + 31) / 32, kb = item / nblk, nb = item % nblk, k0 = 64 * kb, n0 = 32 * nb;
;     const int nn = n0 + (lane & 31); const bool okr = nn < N && nn >= nmin;
;     float m = 0.f;
; #pragma unroll
;     for (int i = 0; i < 32; ++i) { const int kk = 2 * i + (lane >> 5); m = fmaxf(m, fabsf(okr ? W[(size_t)(k0 + kk) * N + nn] : 0.f)); }
;     return m;
.LBB0_279:
	s_load_dwordx2 s[12:13], s[14:15], 0x20
	s_lshl_b64 s[30:31], s[26:27], 2
	v_lshlrev_b32_e32 v6, 2, v2
	s_waitcnt lgkmcnt(0)
	s_add_u32 s12, s12, s30
	s_addc_u32 s13, s13, s31
	v_lshl_add_u64 v[20:21], s[12:13], 0, v[6:7]
	v_lshlrev_b32_e32 v6, 2, v12
	v_lshl_add_u64 v[20:21], v[20:21], 0, v[6:7]
	s_movk_i32 s12, 0x4000
	v_add_co_u32_e32 v22, vcc, 0x4000, v20
	s_nop 1
	v_addc_co_u32_e32 v23, vcc, 0, v21, vcc
	v_add_co_u32_e32 v24, vcc, 0x8000, v20
	s_nop 1
	v_addc_co_u32_e32 v25, vcc, 0, v21, vcc
	v_add_co_u32_e32 v26, vcc, 0xc000, v20
	s_nop 1
	v_addc_co_u32_e32 v27, vcc, 0, v21, vcc
	v_add_co_u32_e32 v28, vcc, 0x10000, v20
	s_nop 1
	v_addc_co_u32_e32 v29, vcc, 0, v21, vcc
	v_add_co_u32_e32 v98, vcc, 0x14000, v20
	s_nop 1
	v_addc_co_u32_e32 v99, vcc, 0, v21, vcc
	v_add_co_u32_e32 v100, vcc, 0x18000, v20
	s_nop 1
	v_addc_co_u32_e32 v101, vcc, 0, v21, vcc
	v_add_co_u32_e32 v102, vcc, 0x1c000, v20
	s_nop 1
	v_addc_co_u32_e32 v103, vcc, 0, v21, vcc
	global_load_dword v6, v[20:21], off
	global_load_dword v97, v[22:23], off
	global_load_dword v106, v[24:25], off
	global_load_dword v107, v[26:27], off
	global_load_dword v108, v[28:29], off
	global_load_dword v109, v[98:99], off
	global_load_dword v110, v[100:101], off
	global_load_dword v111, v[102:103], off
	v_add_co_u32_e32 v22, vcc, 0x20000, v20
	s_nop 1
	v_addc_co_u32_e32 v23, vcc, 0, v21, vcc
	v_add_co_u32_e32 v24, vcc, 0x24000, v20
	s_nop 1
	v_addc_co_u32_e32 v25, vcc, 0, v21, vcc
	v_add_co_u32_e32 v26, vcc, 0x28000, v20
	s_nop 1
	v_addc_co_u32_e32 v27, vcc, 0, v21, vcc
	v_add_co_u32_e32 v28, vcc, s60, v20
	s_nop 1
	v_addc_co_u32_e32 v29, vcc, 0, v21, vcc
	v_add_co_u32_e32 v98, vcc, 0x30000, v20
	s_nop 1
	v_addc_co_u32_e32 v99, vcc, 0, v21, vcc
	v_add_co_u32_e32 v100, vcc, 0x34000, v20
	s_nop 1
	v_addc_co_u32_e32 v101, vcc, 0, v21, vcc
	v_add_co_u32_e32 v102, vcc, s63, v20
	s_nop 1
	v_addc_co_u32_e32 v103, vcc, 0, v21, vcc
	v_add_co_u32_e32 v104, vcc, s64, v20
	s_nop 1
	v_addc_co_u32_e32 v105, vcc, 0, v21, vcc
	global_load_dword v112, v[22:23], off
	global_load_dword v113, v[24:25], off
	global_load_dword v114, v[26:27], off
	global_load_dword v115, v[28:29], off
	global_load_dword v116, v[98:99], off
	global_load_dword v117, v[100:101], off
	global_load_dword v118, v[102:103], off
	global_load_dword v119, v[104:105], off
	s_waitcnt vmcnt(14)
	v_max3_f32 v6, |v6|, 0, |v97|
	s_waitcnt vmcnt(12)
	v_max3_f32 v6, v6, |v106|, |v107|
	s_waitcnt vmcnt(10)
	v_max3_f32 v6, v6, |v108|, |v109|
	s_waitcnt vmcnt(8)
	v_max3_f32 v6, v6, |v110|, |v111|
	v_add_co_u32_e32 v22, vcc, s65, v20
	s_nop 1
	v_addc_co_u32_e32 v23, vcc, 0, v21, vcc
	v_add_co_u32_e32 v24, vcc, s66, v20
	s_nop 1
	v_addc_co_u32_e32 v25, vcc, 0, v21, vcc
	v_add_co_u32_e32 v26, vcc, s67, v20
	s_nop 1
	v_addc_co_u32_e32 v27, vcc, 0, v21, vcc
	v_add_co_u32_e32 v28, vcc, s68, v20
	s_nop 1
	v_addc_co_u32_e32 v29, vcc, 0, v21, vcc
	v_add_co_u32_e32 v98, vcc, s69, v20
	s_nop 1
	v_addc_co_u32_e32 v99, vcc, 0, v21, vcc
	v_add_co_u32_e32 v100, vcc, s72, v20
	s_nop 1
	v_addc_co_u32_e32 v101, vcc, 0, v21, vcc
	v_add_co_u32_e32 v102, vcc, s73, v20
	s_nop 1
	v_addc_co_u32_e32 v103, vcc, 0, v21, vcc
	v_add_co_u32_e32 v104, vcc, s74, v20
	s_nop 1
	v_addc_co_u32_e32 v105, vcc, 0, v21, vcc
	global_load_dword v120, v[22:23], off
	global_load_dword v121, v[24:25], off
	global_load_dword v122, v[26:27], off
	global_load_dword v123, v[28:29], off
	global_load_dword v124, v[98:99], off
	global_load_dword v125, v[100:101], off
	global_load_dword v126, v[102:103], off
	s_nop 0
	global_load_dword v104, v[104:105], off
	s_waitcnt vmcnt(14)
	v_max3_f32 v6, v6, |v112|, |v113|
	s_waitcnt vmcnt(12)
	v_max3_f32 v6, v6, |v114|, |v115|
	s_waitcnt vmcnt(10)
	v_max3_f32 v6, v6, |v116|, |v117|
	s_waitcnt vmcnt(8)
	v_max3_f32 v6, v6, |v118|, |v119|
	v_add_co_u32_e32 v22, vcc, s75, v20
	s_nop 1
	v_addc_co_u32_e32 v23, vcc, 0, v21, vcc
	v_add_co_u32_e32 v24, vcc, s76, v20
	s_nop 1
	v_addc_co_u32_e32 v25, vcc, 0, v21, vcc
	v_add_co_u32_e32 v26, vcc, s77, v20
	s_nop 1
	v_addc_co_u32_e32 v27, vcc, 0, v21, vcc
	v_add_co_u32_e32 v28, vcc, s78, v20
	s_nop 1
	v_addc_co_u32_e32 v29, vcc, 0, v21, vcc
	v_add_co_u32_e32 v98, vcc, s79, v20
	s_nop 1
	v_addc_co_u32_e32 v99, vcc, 0, v21, vcc
	v_add_co_u32_e32 v100, vcc, s80, v20
	s_nop 1
	v_addc_co_u32_e32 v101, vcc, 0, v21, vcc
	v_add_co_u32_e32 v102, vcc, s81, v20
	s_nop 1
	v_addc_co_u32_e32 v103, vcc, 0, v21, vcc
	v_add_co_u32_e32 v20, vcc, s82, v20
	s_nop 1
	v_addc_co_u32_e32 v21, vcc, 0, v21, vcc
	global_load_dword v22, v[22:23], off
	s_nop 0
	global_load_dword v23, v[24:25], off
	s_nop 0
	global_load_dword v24, v[26:27], off
	global_load_dword v25, v[28:29], off
	s_nop 0
	global_load_dword v26, v[98:99], off
	global_load_dword v27, v[100:101], off
	global_load_dword v28, v[102:103], off
	s_nop 0
	global_load_dword v20, v[20:21], off
	s_waitcnt vmcnt(14)
	v_max3_f32 v6, v6, |v120|, |v121|
	s_waitcnt vmcnt(12)
	v_max3_f32 v6, v6, |v122|, |v123|
	s_waitcnt vmcnt(10)
	v_max3_f32 v6, v6, |v124|, |v125|
	s_waitcnt vmcnt(8)
	v_max3_f32 v6, v6, |v126|, |v104|
	s_mov_b32 s12, 0x34000
	v_cmp_lt_i32_e32 vcc, v11, v15
	s_waitcnt vmcnt(6)
	v_max3_f32 v6, v6, |v22|, |v23|
	v_cndmask_b32_e32 v11, v93, v11, vcc
	s_waitcnt vmcnt(4)
	v_max3_f32 v6, v6, |v24|, |v25|
	v_lshlrev_b32_e32 v11, 2, v11
	s_waitcnt vmcnt(2)
	v_max3_f32 v6, v6, |v26|, |v27|
	v_cmp_lt_i32_e32 vcc, v14, v15
	s_waitcnt vmcnt(0)
	v_max3_f32 v6, v6, |v28|, |v20|
	ds_bpermute_b32 v11, v11, v6
	s_waitcnt lgkmcnt(0)
	v_max_f32_e32 v11, v11, v11
	v_max_f32_e32 v6, v6, v11
	v_cndmask_b32_e32 v11, v93, v14, vcc
	v_lshlrev_b32_e32 v11, 2, v11
	ds_bpermute_b32 v11, v11, v6
	v_cmp_lt_i32_e32 vcc, v16, v15
	s_waitcnt lgkmcnt(0)
	v_max_f32_e32 v11, v11, v11
	v_max_f32_e32 v6, v6, v11
	v_cndmask_b32_e32 v11, v93, v16, vcc
	v_lshlrev_b32_e32 v11, 2, v11
	ds_bpermute_b32 v11, v11, v6
	v_cmp_lt_i32_e32 vcc, v17, v15
	s_waitcnt lgkmcnt(0)
	v_max_f32_e32 v11, v11, v11
	v_max_f32_e32 v6, v6, v11
	v_cndmask_b32_e32 v11, v93, v17, vcc
	v_lshlrev_b32_e32 v11, 2, v11
	ds_bpermute_b32 v11, v11, v6
	v_cmp_lt_i32_e32 vcc, v18, v15
	s_waitcnt lgkmcnt(0)
	v_max_f32_e32 v11, v11, v11
	v_max_f32_e32 v6, v6, v11
	v_cndmask_b32_e32 v11, v93, v18, vcc
	v_lshlrev_b32_e32 v11, 2, v11
	ds_bpermute_b32 v11, v11, v6
	v_cmp_lt_i32_e32 vcc, v19, v15
	s_waitcnt lgkmcnt(0)
	v_max_f32_e32 v11, v11, v11
	v_max_f32_e32 v6, v6, v11
	v_cndmask_b32_e32 v11, v93, v19, vcc
	v_lshlrev_b32_e32 v11, 2, v11
	ds_bpermute_b32 v11, v11, v6
	s_waitcnt lgkmcnt(0)
	v_max_f32_e32 v11, v11, v11
	v_max_f32_e32 v14, v6, v11
	v_mul_f32_e32 v6, 0x41000000, v14
	v_max_f32_e32 v6, 0xda24260, v6
	v_div_scale_f32 v11, s[12:13], v6, v6, s47
	v_rcp_f32_e32 v15, v11
	s_nop 0
	v_fma_f32 v16, -v11, v15, 1.0
	v_fmac_f32_e32 v15, v16, v15
	v_div_scale_f32 v16, vcc, s47, v6, s47
	v_mul_f32_e32 v17, v16, v15
	v_fma_f32 v18, -v11, v17, v16
	v_fmac_f32_e32 v17, v18, v15
	v_fma_f32 v11, -v11, v17, v16
	v_div_fmas_f32 v11, v11, v15, v17
	s_and_saveexec_b64 s[30:31], s[38:39]
	s_cbranch_execz .LBB0_284
	s_mov_b64 s[36:37], exec
	s_mov_b32 s12, 0
